# input f32->bf16 convert loop unrolled x4 with 8 loads in flight per thread (trip count 32 per thread at the fixed 512x256 launch)
# baseline (speedup 1.0000x reference)
; DI unsigned pack2(float a, float b) { f32x2_t x = {a, b}; return __builtin_bit_cast(unsigned, __builtin_convertvector(x, bf16x2_t)); }
; DI size_t kblk(size_t M, size_t m, int k) { return ((size_t)(k >> 5) * M + m) * 32 + (k & 31); }
; DI void convert_flat(const float* __restrict__ src, u16* __restrict__ dst, size_t n) {
;   size_t nv = n / 8;
;   for (size_t i = (size_t)blockIdx.x * NTHREADS + threadIdx.x; i < nv; i += (size_t)gridDim.x * NTHREADS) {
;     float4 a = *(const float4*)(src + i * 8), b = *(const float4*)(src + i * 8 + 4);
;     uint4 o; o.x = pack2(a.x, a.y); o.y = pack2(a.z, a.w); o.z = pack2(b.x, b.y); o.w = pack2(b.z, b.w);
;     const size_t e = i * 8, m = e >> 10; const int k = (int)(e & 1023);
;     *(uint4*)(dst + kblk(n >> 10, m, k)) = o;
;   }
; }
.LBB0_7:
	global_load_dwordx4 v[18:21], v[14:15], off offset:-16
	global_load_dwordx4 v[22:25], v[14:15], off
	v_lshrrev_b64 v[26:27], 7, v[16:17]
	v_and_b32_e32 v8, 0xf8000, v10
	v_lshl_add_u64 v[26:27], v[8:9], 0, v[26:27]
	v_and_b32_e32 v1, 24, v12
	v_lshl_add_u64 v[16:17], v[16:17], 0, s[14:15]
	v_lshlrev_b64 v[26:27], 6, v[26:27]
	v_lshlrev_b32_e32 v8, 1, v1
	v_lshl_add_u64 v[26:27], s[12:13], 0, v[26:27]
	v_lshl_add_u64 v[10:11], v[10:11], 0, s[16:17]
	v_lshl_add_u64 v[12:13], v[12:13], 0, s[18:19]
	v_lshl_add_u64 v[14:15], v[14:15], 0, s[20:21]
	v_lshl_add_u64 v[26:27], v[26:27], 0, v[8:9]
	global_load_dwordx4 v[28:31], v[14:15], off offset:-16
	global_load_dwordx4 v[32:35], v[14:15], off
	v_lshrrev_b64 v[52:53], 7, v[16:17]
	v_and_b32_e32 v8, 0xf8000, v10
	v_lshl_add_u64 v[52:53], v[8:9], 0, v[52:53]
	v_and_b32_e32 v1, 24, v12
	v_lshl_add_u64 v[16:17], v[16:17], 0, s[14:15]
	v_lshlrev_b64 v[52:53], 6, v[52:53]
	v_lshlrev_b32_e32 v8, 1, v1
	v_lshl_add_u64 v[52:53], s[12:13], 0, v[52:53]
	v_lshl_add_u64 v[10:11], v[10:11], 0, s[16:17]
	v_lshl_add_u64 v[12:13], v[12:13], 0, s[18:19]
	v_lshl_add_u64 v[14:15], v[14:15], 0, s[20:21]
	v_lshl_add_u64 v[52:53], v[52:53], 0, v[8:9]
	global_load_dwordx4 v[36:39], v[14:15], off offset:-16
	global_load_dwordx4 v[40:43], v[14:15], off
	v_lshrrev_b64 v[54:55], 7, v[16:17]
	v_and_b32_e32 v8, 0xf8000, v10
	v_lshl_add_u64 v[54:55], v[8:9], 0, v[54:55]
	v_and_b32_e32 v1, 24, v12
	v_lshl_add_u64 v[16:17], v[16:17], 0, s[14:15]
	v_lshlrev_b64 v[54:55], 6, v[54:55]
	v_lshlrev_b32_e32 v8, 1, v1
	v_lshl_add_u64 v[54:55], s[12:13], 0, v[54:55]
	v_lshl_add_u64 v[10:11], v[10:11], 0, s[16:17]
	v_lshl_add_u64 v[12:13], v[12:13], 0, s[18:19]
	v_lshl_add_u64 v[14:15], v[14:15], 0, s[20:21]
	v_lshl_add_u64 v[54:55], v[54:55], 0, v[8:9]
	global_load_dwordx4 v[44:47], v[14:15], off offset:-16
	global_load_dwordx4 v[48:51], v[14:15], off
	v_lshrrev_b64 v[56:57], 7, v[16:17]
	v_and_b32_e32 v8, 0xf8000, v10
	v_lshl_add_u64 v[56:57], v[8:9], 0, v[56:57]
	v_and_b32_e32 v1, 24, v12
	v_lshl_add_u64 v[16:17], v[16:17], 0, s[14:15]
	v_lshlrev_b64 v[56:57], 6, v[56:57]
	v_lshlrev_b32_e32 v8, 1, v1
	v_cmp_lt_u64_e32 vcc, s[24:25], v[16:17]
	v_lshl_add_u64 v[56:57], s[12:13], 0, v[56:57]
	v_lshl_add_u64 v[10:11], v[10:11], 0, s[16:17]
	v_lshl_add_u64 v[12:13], v[12:13], 0, s[18:19]
	v_lshl_add_u64 v[14:15], v[14:15], 0, s[20:21]
	s_or_b64 s[22:23], vcc, s[22:23]
	v_lshl_add_u64 v[56:57], v[56:57], 0, v[8:9]
	s_waitcnt vmcnt(7)
	v_cvt_pk_bf16_f32 v18, v18, v19
	v_cvt_pk_bf16_f32 v19, v20, v21
	s_waitcnt vmcnt(6)
	v_cvt_pk_bf16_f32 v20, v22, v23
	v_cvt_pk_bf16_f32 v21, v24, v25
	global_store_dwordx4 v[26:27], v[18:21], off
	s_waitcnt vmcnt(5)
	v_cvt_pk_bf16_f32 v28, v28, v29
	v_cvt_pk_bf16_f32 v29, v30, v31
	s_waitcnt vmcnt(4)
	v_cvt_pk_bf16_f32 v30, v32, v33
	v_cvt_pk_bf16_f32 v31, v34, v35
	global_store_dwordx4 v[52:53], v[28:31], off
	s_waitcnt vmcnt(3)
	v_cvt_pk_bf16_f32 v36, v36, v37
	v_cvt_pk_bf16_f32 v37, v38, v39
	s_waitcnt vmcnt(2)
	v_cvt_pk_bf16_f32 v38, v40, v41
	v_cvt_pk_bf16_f32 v39, v42, v43
	global_store_dwordx4 v[54:55], v[36:39], off
	s_waitcnt vmcnt(1)
	v_cvt_pk_bf16_f32 v44, v44, v45
	v_cvt_pk_bf16_f32 v45, v46, v47
	s_waitcnt vmcnt(0)
	v_cvt_pk_bf16_f32 v46, v48, v49
	v_cvt_pk_bf16_f32 v47, v50, v51
	global_store_dwordx4 v[56:57], v[44:47], off
	s_andn2_b64 exec, exec, s[22:23]
	s_cbranch_execnz .LBB0_7
